# diff-attention tile DMA issue simplified: carried scalar row bases + SADDR loads, no per-piece readfirstlane/M0 save-restore
# speedup vs baseline: 1.0153x; 1.0153x over previous
; DI void diff_item(const Params& P, char* lds, int layer, int pair, int qt, int& tab_head) {
;     ...
;     const unsigned lds0 = (unsigned)(uintptr_t)lds;
;     int goff[2];
; #pragma unroll
;     for (int i = 0; i < 2; ++i) goff[i] = (8 * w + 4 * i + (lane >> 4)) * PO + (((lane & 15) ^ (((lane >> 4) << 2) | ((2 * w + i) & 3))) * 8);
;     const u16* kg = base + head * 128 + OFF_CK;
;     const u16* vg = base + head * 128 + OFF_CV;
;     auto issue = [&](int kt, int buf) {
;         const size_t to = (size_t)(64 * kt) * PO;
; #pragma unroll
;         for (int i = 0; i < 2; ++i) {
;             glds16(kg + to + goff[i], (unsigned)__builtin_amdgcn_readfirstlane(lds0 + buf * 32768 + (2 * w + i) * 1024));
;             glds16(vg + to + goff[i], (unsigned)__builtin_amdgcn_readfirstlane(lds0 + buf * 32768 + 16384 + (2 * w + i) * 1024));
;         }
;     };
;     issue(0, 0);
;     bf16x8 qf[4];
; #pragma unroll
;     for (int s = 0; s < 4; ++s) qf[s] = *(const bf16x8*)(base + (size_t)qpos * PO + OFF_CQ + head * 128 + mp * 64 + 16 * s + 8 * hh);
;     float m = -1e30f, l = 0.f;
;     f32x16 O[4];
; #pragma unroll
;     for (int dt = 0; dt < 4; ++dt)
; #pragma unroll
;         for (int i = 0; i < 16; ++i) O[dt][i] = 0.f;
;     const int sig_r = ((r & 3) << 2) | ((r >> 2) & 3);
;     const int kx0 = (8 * mp + hh) ^ sig_r;
;     const int i16 = lane & 15, q = i16 >> 2, pp = i16 & 3, blk = (lane >> 4) & 1;
;     const int vl0 = (4 * hh + q) * 256 + (16 * ((q << 2) | (blk << 1) | ((pp >> 1) ^ hh)) + 8 * (pp & 1));
;     const int nkt = 2 * qt + 2;
.LBB0_250:
	s_or_b64 exec, exec, s[0:1]
	v_ashrrev_i32_e32 v169, 6, v168
	v_mov_b64_e32 v[2:3], s[20:21]
	s_waitcnt vmcnt(0)
	flat_load_dword v198, v[2:3]
	v_bfe_u32 v2, v168, 4, 2
	v_lshlrev_b32_e32 v7, 1, v169
	v_lshl_or_b32 v3, v169, 3, v2
	v_lshlrev_b32_e32 v2, 2, v2
	v_and_b32_e32 v7, 2, v7
	v_and_b32_e32 v6, 15, v168
	v_or_b32_e32 v9, v7, v2
	v_mul_lo_u32 v3, v3, s67
	v_bitop3_b32 v2, v7, v6, v2 bitop3:0x36
	v_bitop3_b32 v6, v9, v6, 1 bitop3:0x36
	v_lshl_or_b32 v2, v2, 3, v3
	v_lshlrev_b32_e32 v6, 3, v6
	s_sub_i32 s22, 63, s25
	v_add3_u32 v6, v3, v6, s43
	v_ashrrev_i32_e32 v3, 31, v2
	v_lshlrev_b64 v[170:171], 1, v[2:3]
	v_lshlrev_b32_e32 v9, 11, v169
	s_cmp_lg_u32 0, -1
	v_lshl_add_u64 v[2:3], s[96:97], 0, v[170:171]
	v_readfirstlane_b32 s0, v9
	s_cselect_b32 s23, 0, 0
	v_ashrrev_i32_e32 v7, 31, v6
	v_and_b32_e32 v194, 3, v169
	s_add_i32 s1, s0, s23
	s_mov_b32 s16, m0
	s_mov_b32 m0, s1
	s_nop 0
	global_load_lds_dwordx4 v[2:3], off
	s_mov_b32 m0, s16
	v_lshl_add_u64 v[2:3], s[14:15], 0, v[170:171]
	s_add_i32 s40, s23, 0x4000
	v_lshlrev_b64 v[172:173], 1, v[6:7]
	v_lshlrev_b32_e32 v5, 5, v194
	s_add_i32 s1, s0, s40
	s_mov_b32 s16, m0
	s_mov_b32 m0, s1
	s_nop 0
	global_load_lds_dwordx4 v[2:3], off
	s_mov_b32 m0, s16
	v_lshl_add_u64 v[2:3], s[96:97], 0, v[172:173]
	s_add_i32 s41, s23, 0x400
	v_and_b32_e32 v195, 31, v168
	v_lshl_or_b32 v8, s22, 7, v5
	s_add_i32 s1, s0, s41
	s_mov_b32 s16, m0
	s_mov_b32 m0, s1
	s_nop 0
	global_load_lds_dwordx4 v[2:3], off
	s_mov_b32 m0, s16
	v_lshl_add_u64 v[2:3], s[14:15], 0, v[172:173]
	s_add_i32 s51, s23, 0x4400
	v_or_b32_e32 v0, v8, v195
	s_add_i32 s0, s0, s51
	s_mov_b32 s1, m0
	s_mov_b32 m0, s0
	s_nop 0
	global_load_lds_dwordx4 v[2:3], off
	s_mov_b32 m0, s1
	v_mov_b64_e32 v[2:3], s[58:59]
	v_mad_u64_u32 v[166:167], s[0:1], v0, s52, v[2:3]
	s_lshl_b32 s16, s24, 1
	v_ashrrev_i32_e32 v197, 8, v168
	v_lshl_add_u64 v[2:3], v[166:167], 0, s[16:17]
	s_mov_b64 s[0:1], 0x1b00
	v_lshl_add_u64 v[164:165], v[2:3], 0, s[0:1]
	v_lshlrev_b32_e32 v2, 6, v197
	v_bfe_u32 v196, v168, 5, 1
	v_ashrrev_i32_e32 v3, 31, v2
	v_lshl_add_u64 v[2:3], v[2:3], 1, v[164:165]
	v_lshlrev_b32_e32 v0, 4, v196
	v_lshl_add_u64 v[2:3], v[2:3], 0, v[0:1]
	flat_load_dwordx4 v[144:147], v[2:3]
	flat_load_dwordx4 v[148:151], v[2:3] offset:32
	flat_load_dwordx4 v[152:155], v[2:3] offset:64
	flat_load_dwordx4 v[156:159], v[2:3] offset:96
	v_bfe_u32 v2, v168, 2, 2
	v_and_or_b32 v3, v4, 12, v2
	v_lshlrev_b32_e32 v4, 3, v197
	v_lshlrev_b32_e32 v193, 2, v196
	v_lshrrev_b32_e32 v6, 3, v168
	v_lshrrev_b32_e32 v7, 1, v168
	v_bitop3_b32 v3, v4, v3, v196 bitop3:0x36
	v_or_b32_e32 v4, v193, v2
	v_lshlrev_b32_e32 v2, 2, v2
	v_and_b32_e32 v6, 2, v6
	v_bitop3_b32 v7, v7, v196, 1 bitop3:0x6c
	v_or3_b32 v2, v2, v6, v7
	v_lshlrev_b32_e32 v6, 3, v168
	v_and_b32_e32 v6, 8, v6
	v_lshlrev_b32_e32 v4, 8, v4
	v_lshl_or_b32 v2, v2, 4, v6
	s_movk_i32 s0, 0x60
	v_bitop3_b32 v212, v2, s0, v4 bitop3:0x36
	s_movk_i32 s0, 0x80
	v_bitop3_b32 v213, v2, s0, v4 bitop3:0x36
	s_movk_i32 s0, 0xa0
	v_bitop3_b32 v214, v2, s0, v4 bitop3:0x36
	s_movk_i32 s0, 0xc0
	v_bitop3_b32 v215, v2, s0, v4 bitop3:0x36
	s_movk_i32 s0, 0xe0
	v_bitop3_b32 v216, v2, s0, v4 bitop3:0x36
	s_lshl_b32 s0, s25, 7
	v_or_b32_e32 v199, v2, v4
	v_bitop3_b32 v210, v2, 32, v4 bitop3:0x36
	v_bitop3_b32 v211, v2, 64, v4 bitop3:0x36
	v_subrev_u32_e32 v2, s0, v5
	v_add_u32_e32 v217, 0x1f41, v2
	v_lshlrev_b32_e32 v2, 2, v195
	v_lshl_or_b32 v2, v194, 7, v2
	v_sub_u32_e32 v0, v2, v0
	s_lshl_b32 s0, s25, 9
	s_lshl_b32 s49, s22, 1
	v_lshlrev_b32_e32 v6, 8, v168
	v_subrev_u32_e32 v0, s0, v0
	s_add_i32 s0, 0, 0x27e14
	v_mov_b32_e32 v14, v1
	v_mov_b32_e32 v15, v1
	s_add_i32 s49, s49, 2
	v_or_b32_e32 v200, 31, v8
	v_and_b32_e32 v201, 0x1f00, v6
	v_lshlrev_b32_e32 v202, 4, v3
	v_add_u32_e32 v206, s23, v9
	v_add_u32_e32 v207, s40, v9
	v_add_u32_e32 v208, s41, v9
	v_add_u32_e32 v209, s51, v9
	v_add_u32_e32 v218, s0, v0
	v_mov_b32_e32 v0, v1
	v_mov_b32_e32 v2, v1
	v_mov_b32_e32 v3, v1
	v_mov_b32_e32 v4, v1
	v_mov_b32_e32 v5, v1
	v_mov_b32_e32 v6, v1
	v_mov_b32_e32 v7, v1
	v_mov_b32_e32 v8, v1
	v_mov_b32_e32 v9, v1
	v_mov_b32_e32 v10, v1
	v_mov_b32_e32 v11, v1
	v_mov_b32_e32 v12, v1
	v_mov_b32_e32 v13, v1
	v_mov_b64_e32 v[30:31], v[14:15]
	v_mov_b64_e32 v[46:47], v[14:15]
	v_mov_b64_e32 v[62:63], v[14:15]
	v_mov_b64_e32 v[78:79], v[14:15]
	v_xor_b32_e32 v203, 32, v202
	s_mov_b32 s50, 64
	v_xor_b32_e32 v204, 64, v202
	v_xor_b32_e32 v205, 0x60, v202
	s_max_u32 s51, s49, 1
	v_mov_b32_e32 v219, 0
	v_mov_b32_e32 v226, 0xf149f2ca
	s_mov_b32 s25, 0x8000
	v_mov_b32_e32 v220, 0
	s_mov_b64 s[0:1], 0
	v_mov_b64_e32 v[28:29], v[12:13]
	v_mov_b64_e32 v[26:27], v[10:11]
	v_mov_b64_e32 v[24:25], v[8:9]
	v_mov_b64_e32 v[22:23], v[6:7]
	v_mov_b64_e32 v[20:21], v[4:5]
	v_mov_b64_e32 v[18:19], v[2:3]
	v_mov_b64_e32 v[16:17], v[0:1]
	v_mov_b64_e32 v[44:45], v[12:13]
	v_mov_b64_e32 v[42:43], v[10:11]
	v_mov_b64_e32 v[40:41], v[8:9]
	v_mov_b64_e32 v[38:39], v[6:7]
	v_mov_b64_e32 v[36:37], v[4:5]
	v_mov_b64_e32 v[34:35], v[2:3]
	v_mov_b64_e32 v[32:33], v[0:1]
	v_mov_b64_e32 v[60:61], v[12:13]
	v_mov_b64_e32 v[58:59], v[10:11]
	v_mov_b64_e32 v[56:57], v[8:9]
	v_mov_b64_e32 v[54:55], v[6:7]
	v_mov_b64_e32 v[52:53], v[4:5]
	v_mov_b64_e32 v[50:51], v[2:3]
	v_mov_b64_e32 v[48:49], v[0:1]
	v_mov_b64_e32 v[76:77], v[12:13]
	v_mov_b64_e32 v[74:75], v[10:11]
	v_mov_b64_e32 v[72:73], v[8:9]
	v_mov_b64_e32 v[70:71], v[6:7]
	v_mov_b64_e32 v[68:69], v[4:5]
	v_mov_b64_e32 v[66:67], v[2:3]
	v_mov_b64_e32 v[64:65], v[0:1]
	v_readfirstlane_b32 s63, v206
	s_add_u32 s64, s96, 0xe0000
	s_addc_u32 s65, s97, 0
	s_add_u32 s70, s14, 0xe0000
	s_addc_u32 s71, s15, 0
	s_add_i32 s63, s63, 0x8000
	s_mov_b32 s73, m0
	s_branch .LBB0_253

; #define LAS __attribute__((address_space(3)))
; DI void diff_item(const Params& P, char* lds, int layer, int pair, int qt, int& tab_head) {
;     ...
;     auto issue = [&](int kt, int buf) {
;         const size_t to = (size_t)(64 * kt) * PO;
; #pragma unroll
;         for (int i = 0; i < 2; ++i) {
;             glds16(kg + to + goff[i], (unsigned)__builtin_amdgcn_readfirstlane(lds0 + buf * 32768 + (2 * w + i) * 1024));
;             glds16(vg + to + goff[i], (unsigned)__builtin_amdgcn_readfirstlane(lds0 + buf * 32768 + 16384 + (2 * w + i) * 1024));
;         }
;     };
;     ...
;     for (int kt = 0; kt < nkt; ++kt) {
;         asm volatile("s_waitcnt vmcnt(0)" ::: "memory");
;         __syncthreads();
;         auto mid = [&]() { if (kt + 1 < nkt) issue(kt + 1, (kt + 1) & 1); };
;         if (64 * kt <= q0 + 32 * qs + 31) {
;             const bool far = (q0 + 32 * qs) - (64 * kt + 63) >= 1536;
;             const LAS float* tb = (const LAS float*)ctab + (qpos - 64 * kt - 4 * hh + 64 - 63);
;             lptr bufp = (lptr)lds + (kt & 1) * 32768;
;             diff_step(bufp, bufp + 16384, kx0, vl0, qf, m, l, O, tb, far, cfar, lane, mid);
.LBB0_253:
	s_waitcnt vmcnt(0)
	s_sub_i32 s22, s50, 64
	v_cmp_le_u32_e32 vcc, s22, v200
	v_add_u32_e32 v0, 1, v220
	s_waitcnt lgkmcnt(0)
	s_barrier
	s_and_saveexec_b64 s[22:23], vcc
	s_xor_b64 s[40:41], exec, s[22:23]
	s_cbranch_execz .LBB0_263
	s_add_i32 s22, s25, 0xffff8000
	s_and_b32 s22, s22, 0x8000
	s_add_i32 s55, s22, 0
	v_add_u32_e32 v0, s55, v201
	v_add_u32_e32 v2, v0, v202
	s_waitcnt vmcnt(0)
	ds_read_b128 v[80:83], v2
	ds_read_b128 v[84:87], v2 offset:8192
	v_add_u32_e32 v2, v0, v203
	ds_read_b128 v[120:123], v2
	ds_read_b128 v[6:9], v2 offset:8192
	v_add_u32_e32 v2, v0, v204
	v_add_u32_e32 v0, v0, v205
	ds_read_b128 v[116:119], v2
	ds_read_b128 v[2:5], v2 offset:8192
	ds_read_b128 v[10:13], v0
	ds_read_b128 v[112:115], v0 offset:8192
	v_add_u32_e32 v220, 1, v220
	v_cmp_gt_u32_e32 vcc, s49, v220
	s_and_saveexec_b64 s[22:23], vcc
	s_cbranch_execz .LBB0_256
	s_mov_b32 m0, s63
	s_add_u32 s72, s63, 0x4000
	global_load_lds_dwordx4 v170, s[64:65]
	s_mov_b32 m0, s72
	s_add_u32 s72, s63, 0x400
	global_load_lds_dwordx4 v170, s[70:71]
	s_mov_b32 m0, s72
	s_add_u32 s72, s63, 0x4400
	global_load_lds_dwordx4 v172, s[64:65]
	s_mov_b32 m0, s72
	s_xor_b32 s63, s63, 0x8000
	global_load_lds_dwordx4 v172, s[70:71]
	s_add_u32 s64, s64, 0xe0000
	s_addc_u32 s65, s65, 0
	s_add_u32 s70, s70, 0xe0000
	s_addc_u32 s71, s71, 0

; DI void diff_item(const Params& P, char* lds, int layer, int pair, int qt, int& tab_head) {
;     ...
;     auto issue = [&](int kt, int buf) {
;         const size_t to = (size_t)(64 * kt) * PO;
; #pragma unroll
;         for (int i = 0; i < 2; ++i) {
;             glds16(kg + to + goff[i], (unsigned)__builtin_amdgcn_readfirstlane(lds0 + buf * 32768 + (2 * w + i) * 1024));
;             glds16(vg + to + goff[i], (unsigned)__builtin_amdgcn_readfirstlane(lds0 + buf * 32768 + 16384 + (2 * w + i) * 1024));
;         }
;     };
;     ...
;         } else mid();
;     }
;     __syncthreads();
;     const float inv = 1.f / xhalf_sum(l);
;     float* cmb = (float*)lds;
;     if (mp == 1) {
; #pragma unroll
;         for (int dt = 0; dt < 4; ++dt)
; #pragma unroll
;             for (int i = 0; i < 16; ++i) cmb[(qs * 128 + 32 * dt + (i & 3) + 8 * (i >> 2) + 4 * hh) * 32 + r] = O[dt][i] * inv;
.LBB0_263:
	s_andn2_saveexec_b64 s[22:23], s[40:41]
	s_cbranch_execz .LBB0_252
	v_cmp_gt_u32_e32 vcc, s49, v0
	s_and_saveexec_b64 s[40:41], vcc
	s_cbranch_execz .LBB0_251
	s_mov_b32 m0, s63
	s_add_u32 s72, s63, 0x4000
	global_load_lds_dwordx4 v170, s[64:65]
	s_mov_b32 m0, s72
	s_add_u32 s72, s63, 0x400
	global_load_lds_dwordx4 v170, s[70:71]
	s_mov_b32 m0, s72
	s_add_u32 s72, s63, 0x4400
	global_load_lds_dwordx4 v172, s[64:65]
	s_mov_b32 m0, s72
	s_xor_b32 s63, s63, 0x8000
	global_load_lds_dwordx4 v172, s[70:71]
	s_add_u32 s64, s64, 0xe0000
	s_addc_u32 s65, s65, 0
	s_add_u32 s70, s70, 0xe0000
	s_addc_u32 s71, s71, 0
	s_branch .LBB0_251
.LBB0_266:
	s_or_b64 exec, exec, s[0:1]
	s_mov_b32 m0, s73
	v_mov_b32_e32 v0, v219
	s_nop 1
	v_permlane32_swap_b32_e32 v219, v0
	v_add_f32_e32 v0, v219, v0
	v_div_scale_f32 v2, s[0:1], v0, v0, 1.0
	v_rcp_f32_e32 v3, v2
	s_barrier
	v_fma_f32 v4, -v2, v3, 1.0
	v_fmac_f32_e32 v3, v4, v3
	v_div_scale_f32 v4, vcc, 1.0, v0, 1.0
	v_mul_f32_e32 v5, v4, v3
	v_fma_f32 v6, -v2, v5, v4
	v_fmac_f32_e32 v5, v6, v3
	v_fma_f32 v2, -v2, v5, v4
	v_div_fmas_f32 v2, v2, v3, v5
	v_div_fixup_f32 v8, v2, v0, 1.0
	v_cmp_eq_u32_e32 vcc, 1, v197
	v_lshlrev_b32_e32 v2, 9, v196
	v_lshl_add_u32 v3, v195, 2, 0
	s_and_saveexec_b64 s[0:1], vcc
	s_cbranch_execz .LBB0_268
	v_lshlrev_b32_e32 v4, 14, v194
	v_mul_f32_e32 v0, v64, v8
	v_add3_u32 v4, v3, v4, v2
	v_mul_f32_e32 v5, v65, v8
	ds_write2_b32 v4, v0, v5 offset1:32
	v_mul_f32_e32 v0, v66, v8
	v_mul_f32_e32 v5, v67, v8
	ds_write2_b32 v4, v0, v5 offset0:64 offset1:96
	v_mul_f32_e32 v0, v68, v8
	v_mul_f32_e32 v5, v69, v8
	v_add_u32_e32 v6, 0x400, v4
	ds_write2_b32 v6, v0, v5 offset1:32
	v_mul_f32_e32 v0, v70, v8
	v_mul_f32_e32 v5, v71, v8
	ds_write2_b32 v6, v0, v5 offset0:64 offset1:96
	v_mul_f32_e32 v0, v72, v8
	v_mul_f32_e32 v5, v73, v8
	v_add_u32_e32 v6, 0x800, v4
	ds_write2_b32 v6, v0, v5 offset1:32
	v_mul_f32_e32 v0, v74, v8
	v_mul_f32_e32 v5, v75, v8
	ds_write2_b32 v6, v0, v5 offset0:64 offset1:96
	v_mul_f32_e32 v0, v76, v8
	v_mul_f32_e32 v5, v77, v8
	v_add_u32_e32 v6, 0xc00, v4
	ds_write2_b32 v6, v0, v5 offset1:32
	v_mul_f32_e32 v0, v78, v8
	v_mul_f32_e32 v5, v79, v8
	ds_write2_b32 v6, v0, v5 offset0:64 offset1:96
	v_mul_f32_e32 v0, v48, v8
	v_mul_f32_e32 v5, v49, v8
	v_add_u32_e32 v6, 0x1000, v4
	ds_write2_b32 v6, v0, v5 offset1:32
	v_mul_f32_e32 v0, v50, v8
	v_mul_f32_e32 v5, v51, v8
	ds_write2_b32 v6, v0, v5 offset0:64 offset1:96
	v_mul_f32_e32 v0, v52, v8
	v_mul_f32_e32 v5, v53, v8
	v_add_u32_e32 v6, 0x1400, v4
	ds_write2_b32 v6, v0, v5 offset1:32
	v_mul_f32_e32 v0, v54, v8
	v_mul_f32_e32 v5, v55, v8
	ds_write2_b32 v6, v0, v5 offset0:64 offset1:96
	v_mul_f32_e32 v0, v56, v8
	v_mul_f32_e32 v5, v57, v8
	v_add_u32_e32 v6, 0x1800, v4
	ds_write2_b32 v6, v0, v5 offset1:32
	v_mul_f32_e32 v0, v58, v8
	v_mul_f32_e32 v5, v59, v8
	ds_write2_b32 v6, v0, v5 offset0:64 offset1:96
	v_mul_f32_e32 v0, v60, v8
	v_mul_f32_e32 v5, v61, v8
	v_add_u32_e32 v6, 0x1c00, v4
	ds_write2_b32 v6, v0, v5 offset1:32
	v_mul_f32_e32 v0, v62, v8
	v_mul_f32_e32 v5, v63, v8
	ds_write2_b32 v6, v0, v5 offset0:64 offset1:96
	v_mul_f32_e32 v0, v32, v8
	v_mul_f32_e32 v5, v33, v8
	v_add_u32_e32 v6, 0x2000, v4
	ds_write2_b32 v6, v0, v5 offset1:32
	v_mul_f32_e32 v0, v34, v8
	v_mul_f32_e32 v5, v35, v8
	ds_write2_b32 v6, v0, v5 offset0:64 offset1:96
	v_mul_f32_e32 v0, v36, v8
	v_mul_f32_e32 v5, v37, v8
	v_add_u32_e32 v6, 0x2400, v4
	ds_write2_b32 v6, v0, v5 offset1:32
	v_mul_f32_e32 v0, v38, v8
	v_mul_f32_e32 v5, v39, v8
	ds_write2_b32 v6, v0, v5 offset0:64 offset1:96
	v_mul_f32_e32 v0, v40, v8
	v_mul_f32_e32 v5, v41, v8
	v_add_u32_e32 v6, 0x2800, v4
	ds_write2_b32 v6, v0, v5 offset1:32
	v_mul_f32_e32 v0, v42, v8
	v_mul_f32_e32 v5, v43, v8
	ds_write2_b32 v6, v0, v5 offset0:64 offset1:96
	v_mul_f32_e32 v0, v44, v8
	v_mul_f32_e32 v5, v45, v8
	v_add_u32_e32 v6, 0x2c00, v4
	ds_write2_b32 v6, v0, v5 offset1:32
	v_mul_f32_e32 v0, v46, v8
	v_mul_f32_e32 v5, v47, v8
	ds_write2_b32 v6, v0, v5 offset0:64 offset1:96
	v_mul_f32_e32 v0, v16, v8
	v_mul_f32_e32 v5, v17, v8
	v_add_u32_e32 v6, 0x3000, v4
	ds_write2_b32 v6, v0, v5 offset1:32
	v_mul_f32_e32 v0, v18, v8
	v_mul_f32_e32 v5, v19, v8
	ds_write2_b32 v6, v0, v5 offset0:64 offset1:96
	v_mul_f32_e32 v0, v20, v8
	v_mul_f32_e32 v5, v21, v8
	v_add_u32_e32 v6, 0x3400, v4
	ds_write2_b32 v6, v0, v5 offset1:32
	v_mul_f32_e32 v0, v22, v8
	v_mul_f32_e32 v5, v23, v8
	ds_write2_b32 v6, v0, v5 offset0:64 offset1:96
	v_mul_f32_e32 v0, v24, v8
	v_mul_f32_e32 v5, v25, v8
	v_add_u32_e32 v6, 0x3800, v4
	ds_write2_b32 v6, v0, v5 offset1:32
	v_mul_f32_e32 v0, v26, v8
	v_mul_f32_e32 v5, v27, v8
	ds_write2_b32 v6, v0, v5 offset0:64 offset1:96
	v_mul_f32_e32 v0, v28, v8
	v_mul_f32_e32 v5, v29, v8
	v_add_u32_e32 v4, 0x3c00, v4
	ds_write2_b32 v4, v0, v5 offset1:32
	v_mul_f32_e32 v0, v30, v8
	v_mul_f32_e32 v5, v31, v8
	ds_write2_b32 v4, v0, v5 offset0:64 offset1:96
